# DA loop: K second-half reads follow their QK1 MFMA, packs 4 per QK1 gap, V reads ride in QK2 gaps, exp outputs renamed so QK1 leads the iteration
# speedup vs baseline: 1.0380x; 1.0034x over previous
; __device__ __forceinline__ void da_phase(LAS unsigned char* lds, const bf16* Q, const bf16* Kb, const bf16* Vb, bf16* O, const float* lq1, const float* lk1, const float* lq2, const float* lk2,
;                                          const float* t5, int G, int wave, int lane, int tid) {
;     ...
;         const int qrow0 = qb * 128 + 32 * w4;
;         H8 qf[4];
; #pragma unroll
;         for (int d0 = 0; d0 < 4; ++d0) qf[d0] = *(const GASP H8*)(Q + ((size_t)h * T + tok0 + qrow0 + r32) * 128 + comp * 64 + 16 * d0 + 8 * hi);
;         float m = 0.f, l = 0.f; F16 o[4];
; #pragma unroll
;         for (int db = 0; db < 4; ++db) o[db] = F16{};
;         int cur_cls = -1; float cb = 0.f, cbm = 0.f;
;         U4 pw[4] = {};
;         const int NT = S / 64;
;         const char* kub = (const char*)Kb + (((size_t)h * T + tok0 + 32 * (wave & 1)) * 128 + (wave >> 2) * 64 + ((wave >> 1) & 1) * 32) * 2;
;         const char* vub = (const char*)Vb + (((size_t)h * T + tok0 + 16 * ((2 * wave) & 3)) * 128 + ((2 * wave) >> 2) * 32) * 2;
;         const unsigned kofs = (unsigned)(((lane >> 2) * 128 + ((lane & 3) ^ ((lane >> 4) & 3)) * 8) * 2);
;         const unsigned vofs = (unsigned)(((lane >> 2) * 128 + (lane & 3) * 8) * 2);
;     ...
;         DA_DMA(0, 0, 0); DA_DMA(1, 1, 1);
;         int ks_cur = 0, ks_n2 = 2;
;         const unsigned kswz = (unsigned)((hi ^ ((r32 >> 2) & 3)) * 16);
;         const unsigned ka_base = ldsb + KS + comp * 8192 + r32 * 64;
;         S4 va[8], vb[8];
; #pragma unroll 1
;         for (int t = 0; t < NT; ++t) {
;             if (t + 1 < NT) asm volatile("s_waitcnt vmcnt(4)" ::: "memory"); else asm volatile("s_waitcnt vmcnt(0)" ::: "memory");
;             __builtin_amdgcn_s_barrier();
;             asm volatile("" ::: "memory");
;             const unsigned vaddr_p = ldsb + VS + ((t == 0 ? 0 : t + 3) & 3) * 16384 + vlane;
;             U4 kf[4];
;             const unsigned ka0 = ka_base + ks_cur * 16384 + kswz, ka1 = ka_base + ks_cur * 16384 + (kswz ^ 32u);
;             DS_RD128(kf[0], ka0, 0); DS_RD128(kf[1], ka1, 0); DS_RD128(kf[2], ka0, 4096); DS_RD128(kf[3], ka1, 4096);
;             DA_VREADS(va, vaddr_p, 0); DA_VREADS(vb, vaddr_p, 1);
;             const int kv0 = 64 * t; const int relmin = kv0 - (qrow0 + 31), relmax = kv0 + 63 - qrow0;
;             const int cls = 1 + (relmin >= 128 ? 1 : 0) - (relmax <= -128 ? 1 : 0);
.LBB0_201:
	s_lshl_b32 s18, s38, 7
	v_readlane_b32 s0, v254, 47
	s_or_b32 s38, s18, s0
	s_mul_i32 s10, s36, 0x18000
	s_add_u32 s0, s10, s38
	s_addc_u32 s1, 0, 0
	s_add_u32 s0, s0, s14
	s_addc_u32 s1, s1, s15
	v_lshl_add_u64 v[2:3], s[0:1], 0, v[188:189]
	v_readlane_b32 s0, v254, 20
	s_add_u32 s0, s14, s0
	s_addc_u32 s1, s15, 0
	s_add_u32 s0, s0, s10
	s_addc_u32 s1, s1, 0
	s_lshl_b64 s[0:1], s[0:1], 8
	v_lshlrev_b64 v[2:3], 8, v[2:3]
	s_add_u32 s10, s34, s0
	v_lshl_add_u64 v[2:3], v[192:193], 0, v[2:3]
	s_addc_u32 s11, s35, s1
	s_mov_b32 m0, s3
	global_load_dwordx4 v[120:123], v[2:3], off
	global_load_dwordx4 v[124:127], v[2:3], off offset:32
	global_load_dwordx4 v[128:131], v[2:3], off offset:64
	global_load_dwordx4 v[132:135], v[2:3], off offset:96
	s_add_u32 s16, s30, s0
	v_lshl_add_u64 v[2:3], s[10:11], 0, v[194:195]
	s_addc_u32 s17, s31, s1
	global_load_lds_dwordx4 v[2:3], off
	v_lshl_add_u64 v[4:5], v[2:3], 0, s[62:63]
	s_add_i32 m0, s3, 0x400
	s_mov_b64 s[10:11], 0x4000
	global_load_lds_dwordx4 v[4:5], off
	v_lshl_add_u64 v[4:5], s[16:17], 0, v[196:197]
	s_add_i32 m0, s3, 0xc000
	v_lshl_add_u64 v[6:7], v[4:5], 0, s[62:63]
	global_load_lds_dwordx4 v[4:5], off
	s_add_i32 m0, s3, 0xc400
	s_mov_b64 s[16:17], 0x5000
	global_load_lds_dwordx4 v[6:7], off
	v_lshl_add_u64 v[6:7], v[2:3], 0, s[10:11]
	s_add_i32 m0, s3, 0x4000
	v_lshl_add_u64 v[2:3], v[2:3], 0, s[16:17]
	global_load_lds_dwordx4 v[6:7], off
	s_add_i32 m0, s3, 0x4400
	v_add_u32_e32 v0, s18, v228
	global_load_lds_dwordx4 v[2:3], off
	v_lshl_add_u64 v[2:3], v[4:5], 0, s[10:11]
	s_add_i32 s10, 0, 0x10000
	v_readlane_b32 s11, v254, 22
	s_add_i32 m0, s10, s11
	v_readlane_b32 s11, v254, 23
	v_lshl_add_u64 v[2:3], v[4:5], 0, s[16:17]
	s_add_i32 m0, s10, s11
	v_mov_b32_e32 v14, v1
	v_mov_b32_e32 v15, v1
	v_lshl_add_u64 v[202:203], v[198:199], 0, s[0:1]
	v_lshl_add_u64 v[204:205], v[200:201], 0, s[0:1]
	v_sub_u32_e32 v231, v219, v0
	v_readlane_b32 s0, v254, 48
	v_mov_b32_e32 v0, v1
	v_mov_b32_e32 v2, v1
	v_mov_b32_e32 v3, v1
	v_mov_b32_e32 v4, v1
	v_mov_b32_e32 v5, v1
	v_mov_b32_e32 v6, v1
	v_mov_b32_e32 v7, v1
	v_mov_b32_e32 v8, v1
	v_mov_b32_e32 v9, v1
	v_mov_b32_e32 v10, v1
	v_mov_b32_e32 v11, v1
	v_mov_b32_e32 v12, v1
	v_mov_b32_e32 v13, v1
	v_mov_b64_e32 v[30:31], v[14:15]
	v_mov_b64_e32 v[46:47], v[14:15]
	v_mov_b64_e32 v[62:63], v[14:15]
	v_mov_b64_e32 v[78:79], v[14:15]
	v_subrev_u32_e32 v230, s18, v227
	s_sub_i32 s40, s0, s18
	s_lshl_b32 s41, s39, 6
	s_mov_b32 s44, 0
	s_mov_b32 s50, -1
	v_mov_b32_e32 v232, 0
	s_mov_b64 s[16:17], 0
	s_mov_b32 s45, 2
	v_mov_b32_e32 v112, 0
	v_mov_b32_e32 v113, 0
	v_mov_b32_e32 v114, 0
	v_mov_b32_e32 v115, 0
	v_mov_b32_e32 v116, 0
	v_mov_b32_e32 v117, 0
	v_mov_b32_e32 v118, 0
	v_mov_b32_e32 v119, 0
	v_mov_b32_e32 v136, 0
	v_mov_b32_e32 v137, 0
	v_mov_b32_e32 v138, 0
	v_mov_b32_e32 v139, 0
	v_mov_b32_e32 v140, 0
	v_mov_b32_e32 v141, 0
	v_mov_b32_e32 v142, 0
	v_mov_b32_e32 v143, 0
	v_mov_b64_e32 v[28:29], v[12:13]
	v_mov_b64_e32 v[26:27], v[10:11]
	v_mov_b64_e32 v[24:25], v[8:9]
	v_mov_b64_e32 v[22:23], v[6:7]
	v_mov_b64_e32 v[20:21], v[4:5]
	v_mov_b64_e32 v[18:19], v[2:3]
	v_mov_b64_e32 v[16:17], v[0:1]
	v_mov_b64_e32 v[44:45], v[12:13]
	v_mov_b64_e32 v[42:43], v[10:11]
	v_mov_b64_e32 v[40:41], v[8:9]
	v_mov_b64_e32 v[38:39], v[6:7]
	v_mov_b64_e32 v[36:37], v[4:5]
	v_mov_b64_e32 v[34:35], v[2:3]
	v_mov_b64_e32 v[32:33], v[0:1]
	v_mov_b64_e32 v[60:61], v[12:13]
	v_mov_b64_e32 v[58:59], v[10:11]
	v_mov_b64_e32 v[56:57], v[8:9]
	v_mov_b64_e32 v[54:55], v[6:7]
	v_mov_b64_e32 v[52:53], v[4:5]
	v_mov_b64_e32 v[50:51], v[2:3]
	v_mov_b64_e32 v[48:49], v[0:1]
	v_mov_b64_e32 v[76:77], v[12:13]
	v_mov_b64_e32 v[74:75], v[10:11]
	v_mov_b64_e32 v[72:73], v[8:9]
	v_mov_b64_e32 v[70:71], v[6:7]
	v_mov_b64_e32 v[68:69], v[4:5]
	v_mov_b64_e32 v[66:67], v[2:3]
	v_mov_b64_e32 v[64:65], v[0:1]
	v_mov_b32_e32 v229, 0
	v_mov_b32_e32 v233, 0
	v_mov_b32_e32 v14, 0
	s_mov_b32 s46, 0
	s_mov_b32 s47, 2
	s_waitcnt vmcnt(0)
	s_barrier
	s_add_i32 s0, s40, s44
	s_cmpk_gt_i32 s0, 0x9e
	s_cselect_b32 s20, 2, 1
	s_cmpk_lt_i32 s0, 0xff42
	s_cselect_b64 s[0:1], -1, 0
	s_cmp_lg_u64 s[0:1], 0
	s_subb_u32 s51, s20, 0
	s_mov_b64 s[0:1], 0x1b208000
	v_lshl_add_u64 v[204:205], v[204:205], 0, s[0:1]
	s_mov_b64 s[0:1], 0x27204000
	v_lshl_add_u64 v[202:203], v[202:203], 0, s[0:1]
	s_mov_b32 s18, 0xff800000
	s_mov_b32 s21, 0
	v_add_u32_e32 v253, v216, v191
	v_add_u32_e32 v252, v216, v218
	ds_read_b128 v[172:175], v253
	ds_read_b128 v[176:179], v252
	ds_read_b128 v[168:171], v253 offset:4096
	ds_read_b128 v[164:167], v252 offset:4096
	s_waitcnt lgkmcnt(0)
	v_mov_b32_e32 v0, 0
	v_mov_b32_e32 v2, 0
	v_mov_b32_e32 v3, 0
	v_mov_b32_e32 v5, 0
	v_mov_b32_e32 v6, 0
	v_mov_b32_e32 v7, 0
	v_mov_b32_e32 v8, 0
	v_mov_b32_e32 v9, 0
	v_mov_b32_e32 v10, 0
	v_mov_b32_e32 v15, 0
	v_mov_b32_e32 v80, 0
	v_mov_b32_e32 v81, 0
	v_mov_b32_e32 v82, 0
	v_mov_b32_e32 v83, 0
	v_mov_b32_e32 v84, 0
	v_mov_b32_e32 v85, 0
	v_mov_b32_e32 v86, 0
	v_mov_b32_e32 v87, 0
	v_mov_b32_e32 v184, 0
	v_mov_b32_e32 v185, 0
	v_mov_b32_e32 v209, 0
	v_mov_b32_e32 v235, 0
	v_mov_b32_e32 v144, 0
	v_mov_b32_e32 v145, 0
	v_mov_b32_e32 v146, 0
	v_mov_b32_e32 v147, 0
	v_mov_b32_e32 v156, 0
	v_mov_b32_e32 v157, 0
	v_mov_b32_e32 v158, 0
	v_mov_b32_e32 v159, 0
	v_mov_b32_e32 v160, 0
	v_mov_b32_e32 v161, 0
	s_branch .LBB0_204

; #define LGKM_WAIT(n) asm volatile("s_waitcnt lgkmcnt(" #n ")" ::: "memory")
; #define SCHED_FENCE() __builtin_amdgcn_sched_barrier(0)
; #define DA_VREADS(v, vaddr, DB) do { _Pragma("unroll") for (int k_ = 0; k_ < 4; ++k_) { DS_RDTR(v[2 * k_], vaddr, (DB) * 4096 + k_ * 1024); DS_RDTR(v[2 * k_ + 1], vaddr, (DB) * 4096 + k_ * 1024 + 512); } } while (0)
; #define DA_GROUP(v, DB, P, B, acc) do { DA_GAP(v, DB, 0, P, (B), acc); DA_GAP(v, DB, 1, P, (B) + 2, acc); DA_GAP(v, DB, 2, P, (B) + 4, acc); DA_GAP(v, DB, 3, P, (B) + 6, acc); } while (0)
; __device__ __forceinline__ void da_phase(LAS unsigned char* lds, const bf16* Q, const bf16* Kb, const bf16* Vb, bf16* O, const float* lq1, const float* lk1, const float* lq2, const float* lk2,
;                                          const float* t5, int G, int wave, int lane, int tid) {
;     ...
;             float sa = 0.f, sb = 0.f;
;             SCHED_FENCE(); DA_GROUP(va, 0, p0, 0, sa);
;             DA_VREADS(va, vaddr_p, 2); SCHED_FENCE();
;             DA_GROUP(vb, 1, p0, 8, sa);
;             DA_VREADS(vb, vaddr_p, 3); LGKM_WAIT(8); SCHED_FENCE();
;             DA_GROUP(va, 2, p1, 0, sa);
;             LGKM_WAIT(0); SCHED_FENCE();
;             DA_GROUP(vb, 3, p1, 8, sa);
;             l += sa + sb;
.Lda_mid_bar:
	s_waitcnt lgkmcnt(0)
	s_barrier
	v_mfma_f32_32x32x16_bf16 v[64:79], v[140:143], v[160:163], v[64:79]
	v_exp_f32_e32 v0, v96
	v_exp_f32_e32 v15, v97
	s_add_i32 s0, s46, 1
	v_add_f32_e32 v96, v15, v0
	s_cmp_lg_u32 s46, 2
	s_cselect_b32 s46, s0, 0
	v_lshl_add_u32 v252, s46, 14, v216
	v_add_u32_e32 v253, v252, v191
	v_add_u32_e32 v252, v252, v218
	v_mfma_f32_32x32x16_bf16 v[64:79], v[136:139], v[156:159], v[64:79]
	v_exp_f32_e32 v156, v98
	v_exp_f32_e32 v157, v99
	v_add_f32_e32 v96, v156, v96
	v_add_f32_e32 v96, v157, v96
	ds_read_b128 v[172:175], v253
	ds_read_b128 v[176:179], v252
	ds_read_b128 v[168:171], v253 offset:4096
	ds_read_b128 v[164:167], v252 offset:4096
	v_mfma_f32_32x32x16_bf16 v[64:79], v[116:119], v[152:155], v[64:79]
	v_exp_f32_e32 v158, v100
	v_exp_f32_e32 v159, v101
	v_add_f32_e32 v96, v158, v96
	v_add_f32_e32 v96, v159, v96
	s_add_i32 s0, s47, 1
	s_cmp_lg_u32 s47, 2
	s_cselect_b32 s47, s0, 0
	s_and_b32 s21, s16, 0xc000
	v_mfma_f32_32x32x16_bf16 v[64:79], v[112:115], v[148:151], v[64:79]
	v_exp_f32_e32 v160, v102
	v_exp_f32_e32 v161, v103
	v_add_f32_e32 v162, v160, v96
	ds_read_b64_tr_b16 v[96:97], v234 offset:8192
	ds_read_b64_tr_b16 v[98:99], v234 offset:8704
	ds_read_b64_tr_b16 v[100:101], v234 offset:9216
	ds_read_b64_tr_b16 v[102:103], v234 offset:9728
	ds_read_b64_tr_b16 v[148:149], v234 offset:10240
	ds_read_b64_tr_b16 v[150:151], v234 offset:10752
	ds_read_b64_tr_b16 v[152:153], v234 offset:11264
	ds_read_b64_tr_b16 v[154:155], v234 offset:11776
	v_add_f32_e32 v162, v161, v162
	v_mfma_f32_32x32x16_bf16 v[48:63], v[140:143], v[144:147], v[48:63]
	v_exp_f32_e32 v144, v104
	v_exp_f32_e32 v145, v105
	v_add_f32_e32 v104, v144, v162
	v_add_f32_e32 v104, v145, v104
	s_add_u32 s16, s16, 0x4000
	s_addc_u32 s17, s17, 0
	s_add_i32 s45, s45, 1
	s_add_i32 s44, s44, 64
	v_mfma_f32_32x32x16_bf16 v[48:63], v[136:139], v[10:13], v[48:63]
	v_exp_f32_e32 v146, v106
	v_exp_f32_e32 v147, v107
	v_add_f32_e32 v10, v146, v104
	v_add_f32_e32 v10, v147, v10
	s_add_i32 s0, s40, s44
	s_cmpk_gt_i32 s0, 0x9e
	s_cselect_b32 s20, 2, 1
	v_mfma_f32_32x32x16_bf16 v[48:63], v[116:119], v[6:9], v[48:63]
	v_exp_f32_e32 v184, v108
	v_exp_f32_e32 v185, v109
	v_add_f32_e32 v6, v184, v10
	v_add_f32_e32 v6, v185, v6
	s_cmpk_lt_i32 s0, 0xff42
	s_cselect_b64 s[0:1], -1, 0
	s_cmp_lg_u64 s[0:1], 0
	s_subb_u32 s51, s20, 0
	v_mfma_f32_32x32x16_bf16 v[48:63], v[112:115], v[2:5], v[48:63]
	v_exp_f32_e32 v209, v110
	v_exp_f32_e32 v235, v111
	v_add_f32_e32 v162, v209, v6
	ds_read_b64_tr_b16 v[2:3], v234 offset:12288
	ds_read_b64_tr_b16 v[4:5], v234 offset:12800
	ds_read_b64_tr_b16 v[6:7], v234 offset:13312
	ds_read_b64_tr_b16 v[8:9], v234 offset:13824
	ds_read_b64_tr_b16 v[10:11], v234 offset:14336
	ds_read_b64_tr_b16 v[12:13], v234 offset:14848
	ds_read_b64_tr_b16 v[104:105], v234 offset:15360
	ds_read_b64_tr_b16 v[106:107], v234 offset:15872
	s_waitcnt lgkmcnt(8)
	v_add_f32_e32 v162, v235, v162
	v_mfma_f32_32x32x16_bf16 v[32:47], v[140:143], v[96:99], v[32:47]
	v_exp_f32_e32 v80, v80
	v_exp_f32_e32 v81, v81
	v_add_f32_e32 v96, v80, v162
	v_add_f32_e32 v96, v81, v96
	v_mfma_f32_32x32x16_bf16 v[32:47], v[136:139], v[100:103], v[32:47]
	v_exp_f32_e32 v82, v82
	v_exp_f32_e32 v83, v83
	v_add_f32_e32 v96, v82, v96
	v_add_f32_e32 v96, v83, v96
	v_mfma_f32_32x32x16_bf16 v[32:47], v[116:119], v[148:151], v[32:47]
	v_exp_f32_e32 v84, v84
	v_exp_f32_e32 v85, v85
	v_add_f32_e32 v96, v84, v96
	v_add_f32_e32 v96, v85, v96
	v_mfma_f32_32x32x16_bf16 v[32:47], v[112:115], v[152:155], v[32:47]
	v_exp_f32_e32 v86, v86
	v_exp_f32_e32 v87, v87
	v_add_f32_e32 v96, v86, v96
	v_add_f32_e32 v96, v87, v96
	s_waitcnt lgkmcnt(0)
	v_mfma_f32_32x32x16_bf16 v[16:31], v[140:143], v[2:5], v[16:31]
	v_exp_f32_e32 v2, v88
	v_exp_f32_e32 v3, v89
	v_add_f32_e32 v4, v2, v96
	v_add_f32_e32 v4, v3, v4
	v_mfma_f32_32x32x16_bf16 v[16:31], v[136:139], v[6:9], v[16:31]
	v_exp_f32_e32 v5, v90
	v_exp_f32_e32 v6, v91
	v_add_f32_e32 v4, v5, v4
	v_add_f32_e32 v4, v6, v4
	v_mfma_f32_32x32x16_bf16 v[16:31], v[116:119], v[10:13], v[16:31]
	v_exp_f32_e32 v7, v92
	v_exp_f32_e32 v8, v93
	v_add_f32_e32 v4, v7, v4
	v_add_f32_e32 v4, v8, v4
	v_mfma_f32_32x32x16_bf16 v[16:31], v[112:115], v[104:107], v[16:31]
	v_exp_f32_e32 v9, v94
	v_exp_f32_e32 v10, v95
	v_add_f32_e32 v4, v9, v4
	v_add_f32_e32 v4, v10, v4
	v_add_f32_e32 v229, v229, v4
	s_cmp_eq_u32 s41, s44
	s_cbranch_scc1 .LBB0_228

; #define DS_RD128(dst, addr, off) asm volatile("ds_read_b128 %0, %1 offset:%c2" : "=v"(dst) : "v"(addr), "i"(off) : "memory")
; __device__ __forceinline__ void da_phase(LAS unsigned char* lds, const bf16* Q, const bf16* Kb, const bf16* Vb, bf16* O, const float* lq1, const float* lk1, const float* lq2, const float* lk2,
;                                          const float* t5, int G, int wave, int lane, int tid) {
;     ...
;             F16 p0, p1;
;             {   typedef float F2i __attribute__((ext_vector_type(2))); F2i c2 = {cbm, cbm}; asm volatile("" : "+v"(c2));
; #pragma unroll
;                 for (int r = 0; r < 16; r += 2) { p0[r] = c2.x; p0[r + 1] = c2.y; p1[r] = c2.x; p1[r + 1] = c2.y; } }
;             asm volatile("s_waitcnt lgkmcnt(15)" ::: "memory"); SCHED_FENCE();
; #pragma unroll
;             for (int d0 = 0; d0 < 4; ++d0) p0 = __builtin_amdgcn_mfma_f32_32x32x16_bf16(__builtin_bit_cast(H8, kf[d0]), qf[d0], p0, 0, 0, 0);
;             SCHED_FENCE();
;             DS_RD128(kf[0], ka0, 2048); DS_RD128(kf[1], ka1, 2048); DS_RD128(kf[2], ka0, 6144); DS_RD128(kf[3], ka1, 6144);
;             if (t + 2 < NT) DA_DMA_K(t + 2, ks_n2);
;             LGKM_WAIT(0); SCHED_FENCE();
;             float a0;
;             p1 = __builtin_amdgcn_mfma_f32_32x32x16_bf16(__builtin_bit_cast(H8, kf[0]), qf[0], p1, 0, 0, 0); a0 = __builtin_fmaxf(__builtin_fmaxf(p0[0], p0[1]), p0[2]); a0 = __builtin_fmaxf(__builtin_fmaxf(a0, p0[3]), p0[4]); asm volatile("" : "+v"(a0)); SCHED_FENCE();
;             p1 = __builtin_amdgcn_mfma_f32_32x32x16_bf16(__builtin_bit_cast(H8, kf[1]), qf[1], p1, 0, 0, 0); a0 = __builtin_fmaxf(__builtin_fmaxf(a0, p0[5]), p0[6]); a0 = __builtin_fmaxf(__builtin_fmaxf(a0, p0[7]), p0[8]); asm volatile("" : "+v"(a0)); SCHED_FENCE();
;             p1 = __builtin_amdgcn_mfma_f32_32x32x16_bf16(__builtin_bit_cast(H8, kf[2]), qf[2], p1, 0, 0, 0); a0 = __builtin_fmaxf(__builtin_fmaxf(a0, p0[9]), p0[10]); a0 = __builtin_fmaxf(__builtin_fmaxf(a0, p0[11]), p0[12]); asm volatile("" : "+v"(a0)); SCHED_FENCE();
;             p1 = __builtin_amdgcn_mfma_f32_32x32x16_bf16(__builtin_bit_cast(H8, kf[3]), qf[3], p1, 0, 0, 0); a0 = __builtin_fmaxf(__builtin_fmaxf(a0, p0[13]), p0[14]); a0 = __builtin_fmaxf(a0, p0[15]); asm volatile("" : "+v"(a0)); SCHED_FENCE();
;             if (t + 2 < NT) DA_DMA_V(t + 2, (t + 2) & 3);
.LBB0_215:
	v_mfma_f32_32x32x16_bf16 v[96:111], v[172:175], v[120:123], v[236:251]
	ds_read_b128 v[172:175], v252 offset:2048
	v_cvt_pk_bf16_f32 v140, v0, v15
	v_cvt_pk_bf16_f32 v141, v156, v157
	v_cvt_pk_bf16_f32 v142, v158, v159
	v_cvt_pk_bf16_f32 v143, v160, v161
	v_mfma_f32_32x32x16_bf16 v[96:111], v[176:179], v[124:127], v[96:111]
	ds_read_b128 v[176:179], v253 offset:2048
	v_cvt_pk_bf16_f32 v136, v144, v145
	v_cvt_pk_bf16_f32 v137, v146, v147
	v_cvt_pk_bf16_f32 v138, v184, v185
	v_cvt_pk_bf16_f32 v139, v209, v235
	v_mfma_f32_32x32x16_bf16 v[96:111], v[168:171], v[128:131], v[96:111]
	ds_read_b128 v[168:171], v253 offset:6144
	v_cvt_pk_bf16_f32 v116, v80, v81
	v_cvt_pk_bf16_f32 v117, v82, v83
	v_cvt_pk_bf16_f32 v118, v84, v85
	v_cvt_pk_bf16_f32 v119, v86, v87
	v_mfma_f32_32x32x16_bf16 v[96:111], v[164:167], v[132:135], v[96:111]
	ds_read_b128 v[164:167], v252 offset:6144
	v_cvt_pk_bf16_f32 v112, v2, v3
	v_cvt_pk_bf16_f32 v113, v5, v6
	v_cvt_pk_bf16_f32 v114, v7, v8
	v_cvt_pk_bf16_f32 v115, v9, v10
	s_cmp_ge_u32 s45, s39
	s_cbranch_scc1 .LBB0_217
	s_lshl_b32 s0, s47, 14
	s_add_i32 m0, s3, s0
	v_lshl_add_u64 v[182:183], v[204:205], 0, s[62:63]
	global_load_lds_dwordx4 v[204:205], off
	s_add_i32 m0, m0, 0x400
	s_mov_b64 s[0:1], 0x4000
	v_lshl_add_u64 v[204:205], v[204:205], 0, s[0:1]
	global_load_lds_dwordx4 v[182:183], off
.LBB0_217:
	s_waitcnt lgkmcnt(0)
	v_mfma_f32_32x32x16_bf16 v[80:95], v[176:179], v[120:123], v[236:251]
	ds_read_b64_tr_b16 v[160:161], v234 offset:0
	ds_read_b64_tr_b16 v[162:163], v234 offset:512
	ds_read_b64_tr_b16 v[156:157], v234 offset:1024
	ds_read_b64_tr_b16 v[158:159], v234 offset:1536
	v_max3_f32 v0, v96, v97, v98
	v_max3_f32 v0, v0, v99, v100
	v_mfma_f32_32x32x16_bf16 v[80:95], v[172:175], v[124:127], v[80:95]
	ds_read_b64_tr_b16 v[152:153], v234 offset:2048
	ds_read_b64_tr_b16 v[154:155], v234 offset:2560
	ds_read_b64_tr_b16 v[148:149], v234 offset:3072
	ds_read_b64_tr_b16 v[150:151], v234 offset:3584
	v_max3_f32 v0, v0, v101, v102
	v_max3_f32 v0, v0, v103, v104
	v_mfma_f32_32x32x16_bf16 v[80:95], v[168:171], v[128:131], v[80:95]
	ds_read_b64_tr_b16 v[144:145], v234 offset:4096
	ds_read_b64_tr_b16 v[146:147], v234 offset:4608
	ds_read_b64_tr_b16 v[10:11], v234 offset:5120
	ds_read_b64_tr_b16 v[12:13], v234 offset:5632
	v_max3_f32 v0, v0, v105, v106
	v_max3_f32 v0, v0, v107, v108
	v_mfma_f32_32x32x16_bf16 v[80:95], v[164:167], v[132:135], v[80:95]
	ds_read_b64_tr_b16 v[6:7], v234 offset:6144
	ds_read_b64_tr_b16 v[8:9], v234 offset:6656
	ds_read_b64_tr_b16 v[2:3], v234 offset:7168
	ds_read_b64_tr_b16 v[4:5], v234 offset:7680
	v_max_f32_e32 v0, v0, v0
	v_max_f32_e32 v15, v109, v109
	v_max_f32_e32 v0, v0, v15
	v_max3_f32 v0, v0, v110, v111
	s_cmp_gt_u32 s45, s39
	s_cbranch_scc1 .Lda_vskip
	s_add_i32 s0, s16, 0x4000
	s_and_b32 s0, s0, 0xc000
	s_add_i32 s20, s3, s0
	s_add_i32 m0, s20, 0xc000
	v_lshl_add_u64 v[164:165], v[202:203], 0, s[62:63]
	global_load_lds_dwordx4 v[202:203], off
	s_add_i32 m0, m0, 0x400
	s_mov_b64 s[0:1], 0x4000
	v_lshl_add_u64 v[202:203], v[202:203], 0, s[0:1]
	global_load_lds_dwordx4 v[164:165], off

; __device__ __forceinline__ float half_swap_sum(float v) { auto rr = __builtin_amdgcn_permlane32_swap(__float_as_uint(v), __float_as_uint(v), false, false); return __uint_as_float(rr[0]) + __uint_as_float(rr[1]); }
; #define LGKM_WAIT(n) asm volatile("s_waitcnt lgkmcnt(" #n ")" ::: "memory")
; #define SCHED_FENCE() __builtin_amdgcn_sched_barrier(0)
; #define DA_VREADS(v, vaddr, DB) do { _Pragma("unroll") for (int k_ = 0; k_ < 4; ++k_) { DS_RDTR(v[2 * k_], vaddr, (DB) * 4096 + k_ * 1024); DS_RDTR(v[2 * k_ + 1], vaddr, (DB) * 4096 + k_ * 1024 + 512); } } while (0)
; #define DA_VMFMA(v, DB) do { _Pragma("unroll") for (int k_ = 0; k_ < 4; ++k_) { const H8 vf_ = (H8){v[2 * k_][0], v[2 * k_][1], v[2 * k_][2], v[2 * k_][3], v[2 * k_ + 1][0], v[2 * k_ + 1][1], v[2 * k_ + 1][2], v[2 * k_ + 1][3]}; \
;         o[DB] = __builtin_amdgcn_mfma_f32_32x32x16_bf16(__builtin_bit_cast(H8, pw[k_]), vf_, o[DB], 0, 0, 0); } } while (0)
; __device__ __forceinline__ void da_pv(F16 (&o)[4], const U4 (&pw)[4], S4 (&va)[8], S4 (&vb)[8], unsigned vaddr) {
;     LGKM_WAIT(0); SCHED_FENCE(); DA_VMFMA(va, 0); SCHED_FENCE();
;     DA_VREADS(va, vaddr, 2); SCHED_FENCE(); DA_VMFMA(vb, 1); SCHED_FENCE();
;     DA_VREADS(vb, vaddr, 3); LGKM_WAIT(8); SCHED_FENCE(); DA_VMFMA(va, 2); SCHED_FENCE();
;     LGKM_WAIT(0); SCHED_FENCE(); DA_VMFMA(vb, 3); SCHED_FENCE();
; }
; __device__ __forceinline__ void da_phase(LAS unsigned char* lds, const bf16* Q, const bf16* Kb, const bf16* Vb, bf16* O, const float* lq1, const float* lk1, const float* lq2, const float* lk2,
;                                          const float* t5, int G, int wave, int lane, int tid) {
;     ...
;         {   const unsigned vaddr = ldsb + VS + ((NT - 1) & 3) * 16384 + vlane; DA_VREADS(va, vaddr, 0); DA_VREADS(vb, vaddr, 1); da_pv(o, pw, va, vb, vaddr); }
;     ...
;         int lane_e = lane; asm volatile("" : "+v"(lane_e));
;         const int r32e = lane_e & 31, hie = lane_e >> 5;
;         const float lt = half_swap_sum(l);
;         if (hie == 0) wsf[r32e] = (comp == 0 ? 1.0f : -lam) / lt;
.LBB0_228:
	v_cvt_pk_bf16_f32 v140, v0, v15
	v_cvt_pk_bf16_f32 v141, v156, v157
	v_cvt_pk_bf16_f32 v142, v158, v159
	v_cvt_pk_bf16_f32 v143, v160, v161
	v_cvt_pk_bf16_f32 v136, v144, v145
	v_cvt_pk_bf16_f32 v137, v146, v147
	v_cvt_pk_bf16_f32 v138, v184, v185
	v_cvt_pk_bf16_f32 v139, v209, v235
	v_cvt_pk_bf16_f32 v116, v80, v81
	v_cvt_pk_bf16_f32 v117, v82, v83
	v_cvt_pk_bf16_f32 v118, v84, v85
	v_cvt_pk_bf16_f32 v119, v86, v87
	v_cvt_pk_bf16_f32 v112, v2, v3
	v_cvt_pk_bf16_f32 v113, v5, v6
	v_cvt_pk_bf16_f32 v114, v7, v8
	v_cvt_pk_bf16_f32 v115, v9, v10
	ds_read_b64_tr_b16 v[2:3], v221 offset:0
	ds_read_b64_tr_b16 v[4:5], v221 offset:512
	ds_read_b64_tr_b16 v[6:7], v221 offset:1024
	ds_read_b64_tr_b16 v[8:9], v221 offset:1536
	ds_read_b64_tr_b16 v[10:11], v221 offset:2048
	ds_read_b64_tr_b16 v[12:13], v221 offset:2560
	ds_read_b64_tr_b16 v[80:81], v221 offset:3072
	ds_read_b64_tr_b16 v[82:83], v221 offset:3584
	ds_read_b64_tr_b16 v[84:85], v221 offset:4096
	ds_read_b64_tr_b16 v[86:87], v221 offset:4608
	ds_read_b64_tr_b16 v[88:89], v221 offset:5120
	ds_read_b64_tr_b16 v[90:91], v221 offset:5632
	ds_read_b64_tr_b16 v[92:93], v221 offset:6144
	ds_read_b64_tr_b16 v[94:95], v221 offset:6656
	ds_read_b64_tr_b16 v[96:97], v221 offset:7168
	ds_read_b64_tr_b16 v[98:99], v221 offset:7680
	s_waitcnt lgkmcnt(0)
	s_nop 0
	v_mfma_f32_32x32x16_bf16 v[64:79], v[140:143], v[2:5], v[64:79]
	v_mfma_f32_32x32x16_bf16 v[64:79], v[136:139], v[6:9], v[64:79]
	v_mfma_f32_32x32x16_bf16 v[64:79], v[116:119], v[10:13], v[64:79]
	v_mfma_f32_32x32x16_bf16 v[64:79], v[112:115], v[80:83], v[64:79]
	ds_read_b64_tr_b16 v[2:3], v221 offset:8192
	ds_read_b64_tr_b16 v[4:5], v221 offset:8704
	ds_read_b64_tr_b16 v[6:7], v221 offset:9216
	ds_read_b64_tr_b16 v[8:9], v221 offset:9728
	ds_read_b64_tr_b16 v[10:11], v221 offset:10240
	ds_read_b64_tr_b16 v[12:13], v221 offset:10752
	ds_read_b64_tr_b16 v[80:81], v221 offset:11264
	ds_read_b64_tr_b16 v[82:83], v221 offset:11776
	v_mfma_f32_32x32x16_bf16 v[48:63], v[140:143], v[84:87], v[48:63]
	v_mfma_f32_32x32x16_bf16 v[48:63], v[136:139], v[88:91], v[48:63]
	v_mfma_f32_32x32x16_bf16 v[48:63], v[116:119], v[92:95], v[48:63]
	v_mfma_f32_32x32x16_bf16 v[48:63], v[112:115], v[96:99], v[48:63]
	ds_read_b64_tr_b16 v[84:85], v221 offset:12288
	ds_read_b64_tr_b16 v[86:87], v221 offset:12800
	ds_read_b64_tr_b16 v[88:89], v221 offset:13312
	ds_read_b64_tr_b16 v[90:91], v221 offset:13824
	ds_read_b64_tr_b16 v[92:93], v221 offset:14336
	ds_read_b64_tr_b16 v[94:95], v221 offset:14848
	ds_read_b64_tr_b16 v[96:97], v221 offset:15360
	ds_read_b64_tr_b16 v[98:99], v221 offset:15872
	s_waitcnt lgkmcnt(8)
	v_mfma_f32_32x32x16_bf16 v[32:47], v[140:143], v[2:5], v[32:47]
	v_mfma_f32_32x32x16_bf16 v[32:47], v[136:139], v[6:9], v[32:47]
	v_mfma_f32_32x32x16_bf16 v[32:47], v[116:119], v[10:13], v[32:47]
	v_mfma_f32_32x32x16_bf16 v[32:47], v[112:115], v[80:83], v[32:47]
	s_waitcnt lgkmcnt(0)
	v_mfma_f32_32x32x16_bf16 v[16:31], v[140:143], v[84:87], v[16:31]
	v_mfma_f32_32x32x16_bf16 v[16:31], v[136:139], v[88:91], v[16:31]
	v_mfma_f32_32x32x16_bf16 v[16:31], v[116:119], v[92:95], v[16:31]
	v_mfma_f32_32x32x16_bf16 v[16:31], v[112:115], v[96:99], v[16:31]
	v_mov_b32_e32 v0, v206
	v_mov_b32_e32 v2, v229
	s_nop 1
	v_permlane32_swap_b32_e32 v229, v2
	v_and_b32_e32 v126, 31, v0
	v_cmp_gt_u32_e32 vcc, 32, v0
	s_and_saveexec_b64 s[0:1], vcc
	s_cbranch_execz .LBB0_230
	v_add_f32_e32 v2, v229, v2
	v_div_scale_f32 v3, s[10:11], v2, v2, v222
	v_rcp_f32_e32 v4, v3
	v_div_scale_f32 v5, vcc, v222, v2, v222
	v_fma_f32 v6, -v3, v4, 1.0
	v_fmac_f32_e32 v4, v6, v4
	v_mul_f32_e32 v6, v5, v4
	v_fma_f32 v7, -v3, v6, v5
	v_fmac_f32_e32 v6, v7, v4
	v_fma_f32 v3, -v3, v6, v5
	v_div_fmas_f32 v3, v3, v4, v6
	v_div_fixup_f32 v2, v3, v2, v222
	v_lshl_add_u32 v3, v126, 2, s99
	ds_write_b32 v3, v2
